# P0 weight transposition: loads of all (up to 5) units issued at once before the LDS transposes; out-proj quarter units mapped XCD-contiguously
# speedup vs baseline: 1.0930x; 1.0098x over previous
; DI unsigned pk2(float a, float b) { f32x2 v = {a, b}; bf16x2v r = __builtin_convertvector(v, bf16x2v); return __builtin_bit_cast(unsigned, r); }
; DI void phase0(const Params& p, char* smem) {
;     ...
;     for (int u = blockIdx.x; u < 1280; u += gridDim.x) {
;         const float* src; int ld; bf16_t* dst;
;         if (u < 1024) { const int kt = u >> 6, nt = u & 63; src = p.w_in + (size_t)(kt * 64) * INW + nt * 64; ld = INW; dst = p.wtin + (size_t)(nt * 64) * DM + kt * 64; }
;         else { const int v = u - 1024, kt = v >> 4, nt = v & 15; src = p.w_out + (size_t)(kt * 64) * DM + nt * 64; ld = DM; dst = p.wtout + (size_t)(nt * 64) * DM + kt * 64; }
; #pragma unroll
;         for (int i = 0; i < 2; ++i) {
;             const int r = (tid >> 4) + 32 * i, c = (tid & 15) * 4;
;             const f32x4 v = *(const f32x4*)(src + (size_t)r * ld + c);
;             tile[r * 65 + c] = v[0]; tile[r * 65 + c + 1] = v[1]; tile[r * 65 + c + 2] = v[2]; tile[r * 65 + c + 3] = v[3];
;         }
;         __syncthreads();
;         {
;             const int n = (tid >> 3), kc = (tid & 7) * 8;
;             u32x4 w;
;             w[0] = pk2(tile[(kc + 0) * 65 + n], tile[(kc + 1) * 65 + n]);
;             w[1] = pk2(tile[(kc + 2) * 65 + n], tile[(kc + 3) * 65 + n]);
;             w[2] = pk2(tile[(kc + 4) * 65 + n], tile[(kc + 5) * 65 + n]);
;             w[3] = pk2(tile[(kc + 6) * 65 + n], tile[(kc + 7) * 65 + n]);
;             *(u32x4*)(dst + (size_t)n * DM + kc) = w;
;         }
;         __syncthreads();
;     }
.Lp0t_start:
	s_mov_b32 s20, 0
	s_cmpk_gt_i32 s19, 0x4ff
	s_cbranch_scc1 .Lp0t_issued
	s_cmpk_gt_i32 s19, 0x3ff
	s_cbranch_scc0 .Lp0t_win_0
	s_and_b32 s4, s17, 0x7fffffc0
	s_addk_i32 s4, 0xf000
	s_lshl_b64 s[6:7], s[4:5], 12
	s_add_u32 s10, s50, s6
	s_addc_u32 s11, s51, s7
	s_mov_b64 s[6:7], s[4:5]
	s_mov_b64 s[8:9], s[64:65]
	s_mov_b64 s[12:13], 0x400
	s_movk_i32 s4, 0x3c0
	s_branch .Lp0t_ld_0
.Lp0t_win_0:
	s_mov_b64 s[8:9], s[62:63]
	s_and_b32 s6, s19, 0xffffffc0
	s_ashr_i32 s7, s6, 31
	s_mul_i32 s10, s6, 0x4020
	s_mul_hi_i32 s4, s6, 0x4020
	s_add_u32 s10, s46, s10
	s_addc_u32 s11, s47, s4
	s_mov_b64 s[12:13], 0x1008
	s_movk_i32 s4, 0xfc0
.Lp0t_ld_0:
	s_and_b32 s4, s15, s4
	s_lshl_b32 s13, s4, 2
	s_add_u32 s10, s10, s13
	s_addc_u32 s11, s11, 0
	v_lshl_add_u64 v[18:19], s[10:11], 0, v[4:5]
	v_mad_i64_i32 v[14:15], s[10:11], s12, v2, 0
	v_lshl_add_u64 v[14:15], v[14:15], 2, v[18:19]
	global_load_dwordx4 v[24:27], v[14:15], off
	v_mad_i64_i32 v[20:21], s[10:11], s12, v8, 0
	v_lshl_add_u64 v[18:19], v[20:21], 2, v[18:19]
	global_load_dwordx4 v[28:31], v[18:19], off
	s_lshl_b32 s4, s4, 11
	s_add_u32 s4, s8, s4
	s_addc_u32 s8, s9, 0
	s_lshl_b64 s[6:7], s[6:7], 1
	s_add_u32 s6, s4, s6
	s_addc_u32 s7, s8, s7
	s_add_i32 s19, s19, s14
	s_add_i32 s15, s15, s16
	s_add_i32 s17, s17, s18
	v_lshl_add_u64 v[68:69], s[6:7], 0, v[6:7]
	v_lshl_add_u64 v[68:69], v[68:69], 0, v[10:11]
	s_bitset1_b32 s20, 0
	s_cmpk_gt_i32 s19, 0x4ff
	s_cbranch_scc1 .Lp0t_issued
	s_cmpk_gt_i32 s19, 0x3ff
	s_cbranch_scc0 .Lp0t_win_1
	s_and_b32 s4, s17, 0x7fffffc0
	s_addk_i32 s4, 0xf000
	s_lshl_b64 s[6:7], s[4:5], 12
	s_add_u32 s10, s50, s6
	s_addc_u32 s11, s51, s7
	s_mov_b64 s[6:7], s[4:5]
	s_mov_b64 s[8:9], s[64:65]
	s_mov_b64 s[12:13], 0x400
	s_movk_i32 s4, 0x3c0
	s_branch .Lp0t_ld_1

; DI unsigned pk2(float a, float b) { f32x2 v = {a, b}; bf16x2v r = __builtin_convertvector(v, bf16x2v); return __builtin_bit_cast(unsigned, r); }
; DI void phase0(const Params& p, char* smem) {
;     ...
;     for (int u = blockIdx.x; u < 1280; u += gridDim.x) {
;         const float* src; int ld; bf16_t* dst;
;         if (u < 1024) { const int kt = u >> 6, nt = u & 63; src = p.w_in + (size_t)(kt * 64) * INW + nt * 64; ld = INW; dst = p.wtin + (size_t)(nt * 64) * DM + kt * 64; }
;         else { const int v = u - 1024, kt = v >> 4, nt = v & 15; src = p.w_out + (size_t)(kt * 64) * DM + nt * 64; ld = DM; dst = p.wtout + (size_t)(nt * 64) * DM + kt * 64; }
; #pragma unroll
;         for (int i = 0; i < 2; ++i) {
;             const int r = (tid >> 4) + 32 * i, c = (tid & 15) * 4;
;             const f32x4 v = *(const f32x4*)(src + (size_t)r * ld + c);
;             tile[r * 65 + c] = v[0]; tile[r * 65 + c + 1] = v[1]; tile[r * 65 + c + 2] = v[2]; tile[r * 65 + c + 3] = v[3];
;         }
;         __syncthreads();
;         {
;             const int n = (tid >> 3), kc = (tid & 7) * 8;
;             u32x4 w;
;             w[0] = pk2(tile[(kc + 0) * 65 + n], tile[(kc + 1) * 65 + n]);
;             w[1] = pk2(tile[(kc + 2) * 65 + n], tile[(kc + 3) * 65 + n]);
;             w[2] = pk2(tile[(kc + 4) * 65 + n], tile[(kc + 5) * 65 + n]);
;             w[3] = pk2(tile[(kc + 6) * 65 + n], tile[(kc + 7) * 65 + n]);
;             *(u32x4*)(dst + (size_t)n * DM + kc) = w;
;         }
;         __syncthreads();
;     }
.Lp0t_ld_1:
	s_and_b32 s4, s15, s4
	s_lshl_b32 s13, s4, 2
	s_add_u32 s10, s10, s13
	s_addc_u32 s11, s11, 0
	v_lshl_add_u64 v[18:19], s[10:11], 0, v[4:5]
	v_mad_i64_i32 v[14:15], s[10:11], s12, v2, 0
	v_lshl_add_u64 v[14:15], v[14:15], 2, v[18:19]
	global_load_dwordx4 v[32:35], v[14:15], off
	v_mad_i64_i32 v[20:21], s[10:11], s12, v8, 0
	v_lshl_add_u64 v[18:19], v[20:21], 2, v[18:19]
	global_load_dwordx4 v[36:39], v[18:19], off
	s_lshl_b32 s4, s4, 11
	s_add_u32 s4, s8, s4
	s_addc_u32 s8, s9, 0
	s_lshl_b64 s[6:7], s[6:7], 1
	s_add_u32 s6, s4, s6
	s_addc_u32 s7, s8, s7
	s_add_i32 s19, s19, s14
	s_add_i32 s15, s15, s16
	s_add_i32 s17, s17, s18
	v_lshl_add_u64 v[70:71], s[6:7], 0, v[6:7]
	v_lshl_add_u64 v[70:71], v[70:71], 0, v[10:11]
	s_bitset1_b32 s20, 1
	s_cmpk_gt_i32 s19, 0x4ff
	s_cbranch_scc1 .Lp0t_issued
	s_cmpk_gt_i32 s19, 0x3ff
	s_cbranch_scc0 .Lp0t_win_2
	s_and_b32 s4, s17, 0x7fffffc0
	s_addk_i32 s4, 0xf000
	s_lshl_b64 s[6:7], s[4:5], 12
	s_add_u32 s10, s50, s6
	s_addc_u32 s11, s51, s7
	s_mov_b64 s[6:7], s[4:5]
	s_mov_b64 s[8:9], s[64:65]
	s_mov_b64 s[12:13], 0x400
	s_movk_i32 s4, 0x3c0
	s_branch .Lp0t_ld_2

; DI unsigned pk2(float a, float b) { f32x2 v = {a, b}; bf16x2v r = __builtin_convertvector(v, bf16x2v); return __builtin_bit_cast(unsigned, r); }
; DI void phase0(const Params& p, char* smem) {
;     ...
;     for (int u = blockIdx.x; u < 1280; u += gridDim.x) {
;         const float* src; int ld; bf16_t* dst;
;         if (u < 1024) { const int kt = u >> 6, nt = u & 63; src = p.w_in + (size_t)(kt * 64) * INW + nt * 64; ld = INW; dst = p.wtin + (size_t)(nt * 64) * DM + kt * 64; }
;         else { const int v = u - 1024, kt = v >> 4, nt = v & 15; src = p.w_out + (size_t)(kt * 64) * DM + nt * 64; ld = DM; dst = p.wtout + (size_t)(nt * 64) * DM + kt * 64; }
; #pragma unroll
;         for (int i = 0; i < 2; ++i) {
;             const int r = (tid >> 4) + 32 * i, c = (tid & 15) * 4;
;             const f32x4 v = *(const f32x4*)(src + (size_t)r * ld + c);
;             tile[r * 65 + c] = v[0]; tile[r * 65 + c + 1] = v[1]; tile[r * 65 + c + 2] = v[2]; tile[r * 65 + c + 3] = v[3];
;         }
;         __syncthreads();
;         {
;             const int n = (tid >> 3), kc = (tid & 7) * 8;
;             u32x4 w;
;             w[0] = pk2(tile[(kc + 0) * 65 + n], tile[(kc + 1) * 65 + n]);
;             w[1] = pk2(tile[(kc + 2) * 65 + n], tile[(kc + 3) * 65 + n]);
;             w[2] = pk2(tile[(kc + 4) * 65 + n], tile[(kc + 5) * 65 + n]);
;             w[3] = pk2(tile[(kc + 6) * 65 + n], tile[(kc + 7) * 65 + n]);
;             *(u32x4*)(dst + (size_t)n * DM + kc) = w;
;         }
;         __syncthreads();
;     }
.Lp0t_ld_2:
	s_and_b32 s4, s15, s4
	s_lshl_b32 s13, s4, 2
	s_add_u32 s10, s10, s13
	s_addc_u32 s11, s11, 0
	v_lshl_add_u64 v[18:19], s[10:11], 0, v[4:5]
	v_mad_i64_i32 v[14:15], s[10:11], s12, v2, 0
	v_lshl_add_u64 v[14:15], v[14:15], 2, v[18:19]
	global_load_dwordx4 v[40:43], v[14:15], off
	v_mad_i64_i32 v[20:21], s[10:11], s12, v8, 0
	v_lshl_add_u64 v[18:19], v[20:21], 2, v[18:19]
	global_load_dwordx4 v[44:47], v[18:19], off
	s_lshl_b32 s4, s4, 11
	s_add_u32 s4, s8, s4
	s_addc_u32 s8, s9, 0
	s_lshl_b64 s[6:7], s[6:7], 1
	s_add_u32 s6, s4, s6
	s_addc_u32 s7, s8, s7
	s_add_i32 s19, s19, s14
	s_add_i32 s15, s15, s16
	s_add_i32 s17, s17, s18
	v_lshl_add_u64 v[72:73], s[6:7], 0, v[6:7]
	v_lshl_add_u64 v[72:73], v[72:73], 0, v[10:11]
	s_bitset1_b32 s20, 2
	s_cmpk_gt_i32 s19, 0x4ff
	s_cbranch_scc1 .Lp0t_issued
	s_cmpk_gt_i32 s19, 0x3ff
	s_cbranch_scc0 .Lp0t_win_3
	s_and_b32 s4, s17, 0x7fffffc0
	s_addk_i32 s4, 0xf000
	s_lshl_b64 s[6:7], s[4:5], 12
	s_add_u32 s10, s50, s6
	s_addc_u32 s11, s51, s7
	s_mov_b64 s[6:7], s[4:5]
	s_mov_b64 s[8:9], s[64:65]
	s_mov_b64 s[12:13], 0x400
	s_movk_i32 s4, 0x3c0
	s_branch .Lp0t_ld_3

; DI unsigned pk2(float a, float b) { f32x2 v = {a, b}; bf16x2v r = __builtin_convertvector(v, bf16x2v); return __builtin_bit_cast(unsigned, r); }
; DI void phase0(const Params& p, char* smem) {
;     ...
;     for (int u = blockIdx.x; u < 1280; u += gridDim.x) {
;         const float* src; int ld; bf16_t* dst;
;         if (u < 1024) { const int kt = u >> 6, nt = u & 63; src = p.w_in + (size_t)(kt * 64) * INW + nt * 64; ld = INW; dst = p.wtin + (size_t)(nt * 64) * DM + kt * 64; }
;         else { const int v = u - 1024, kt = v >> 4, nt = v & 15; src = p.w_out + (size_t)(kt * 64) * DM + nt * 64; ld = DM; dst = p.wtout + (size_t)(nt * 64) * DM + kt * 64; }
; #pragma unroll
;         for (int i = 0; i < 2; ++i) {
;             const int r = (tid >> 4) + 32 * i, c = (tid & 15) * 4;
;             const f32x4 v = *(const f32x4*)(src + (size_t)r * ld + c);
;             tile[r * 65 + c] = v[0]; tile[r * 65 + c + 1] = v[1]; tile[r * 65 + c + 2] = v[2]; tile[r * 65 + c + 3] = v[3];
;         }
;         __syncthreads();
;         {
;             const int n = (tid >> 3), kc = (tid & 7) * 8;
;             u32x4 w;
;             w[0] = pk2(tile[(kc + 0) * 65 + n], tile[(kc + 1) * 65 + n]);
;             w[1] = pk2(tile[(kc + 2) * 65 + n], tile[(kc + 3) * 65 + n]);
;             w[2] = pk2(tile[(kc + 4) * 65 + n], tile[(kc + 5) * 65 + n]);
;             w[3] = pk2(tile[(kc + 6) * 65 + n], tile[(kc + 7) * 65 + n]);
;             *(u32x4*)(dst + (size_t)n * DM + kc) = w;
;         }
;         __syncthreads();
;     }
.Lp0t_ld_3:
	s_and_b32 s4, s15, s4
	s_lshl_b32 s13, s4, 2
	s_add_u32 s10, s10, s13
	s_addc_u32 s11, s11, 0
	v_lshl_add_u64 v[18:19], s[10:11], 0, v[4:5]
	v_mad_i64_i32 v[14:15], s[10:11], s12, v2, 0
	v_lshl_add_u64 v[14:15], v[14:15], 2, v[18:19]
	global_load_dwordx4 v[52:55], v[14:15], off
	v_mad_i64_i32 v[20:21], s[10:11], s12, v8, 0
	v_lshl_add_u64 v[18:19], v[20:21], 2, v[18:19]
	global_load_dwordx4 v[56:59], v[18:19], off
	s_lshl_b32 s4, s4, 11
	s_add_u32 s4, s8, s4
	s_addc_u32 s8, s9, 0
	s_lshl_b64 s[6:7], s[6:7], 1
	s_add_u32 s6, s4, s6
	s_addc_u32 s7, s8, s7
	s_add_i32 s19, s19, s14
	s_add_i32 s15, s15, s16
	s_add_i32 s17, s17, s18
	v_lshl_add_u64 v[74:75], s[6:7], 0, v[6:7]
	v_lshl_add_u64 v[74:75], v[74:75], 0, v[10:11]
	s_bitset1_b32 s20, 3
	s_cmpk_gt_i32 s19, 0x4ff
	s_cbranch_scc1 .Lp0t_issued
	s_cmpk_gt_i32 s19, 0x3ff
	s_cbranch_scc0 .Lp0t_win_4
	s_and_b32 s4, s17, 0x7fffffc0
	s_addk_i32 s4, 0xf000
	s_lshl_b64 s[6:7], s[4:5], 12
	s_add_u32 s10, s50, s6
	s_addc_u32 s11, s51, s7
	s_mov_b64 s[6:7], s[4:5]
	s_mov_b64 s[8:9], s[64:65]
	s_mov_b64 s[12:13], 0x400
	s_movk_i32 s4, 0x3c0
	s_branch .Lp0t_ld_4

; DI unsigned pk2(float a, float b) { f32x2 v = {a, b}; bf16x2v r = __builtin_convertvector(v, bf16x2v); return __builtin_bit_cast(unsigned, r); }
; DI void phase0(const Params& p, char* smem) {
;     ...
; #pragma unroll
;         for (int i = 0; i < 2; ++i) {
;             const int r = (tid >> 4) + 32 * i, c = (tid & 15) * 4;
;             const f32x4 v = *(const f32x4*)(src + (size_t)r * ld + c);
;             tile[r * 65 + c] = v[0]; tile[r * 65 + c + 1] = v[1]; tile[r * 65 + c + 2] = v[2]; tile[r * 65 + c + 3] = v[3];
;         }
;         __syncthreads();
;         {
;             const int n = (tid >> 3), kc = (tid & 7) * 8;
;             u32x4 w;
;             w[0] = pk2(tile[(kc + 0) * 65 + n], tile[(kc + 1) * 65 + n]);
;             w[1] = pk2(tile[(kc + 2) * 65 + n], tile[(kc + 3) * 65 + n]);
;             w[2] = pk2(tile[(kc + 4) * 65 + n], tile[(kc + 5) * 65 + n]);
;             w[3] = pk2(tile[(kc + 6) * 65 + n], tile[(kc + 7) * 65 + n]);
;             *(u32x4*)(dst + (size_t)n * DM + kc) = w;
;         }
;         __syncthreads();
;     }
.Lp0t_ld_4:
	s_and_b32 s4, s15, s4
	s_lshl_b32 s13, s4, 2
	s_add_u32 s10, s10, s13
	s_addc_u32 s11, s11, 0
	v_lshl_add_u64 v[18:19], s[10:11], 0, v[4:5]
	v_mad_i64_i32 v[14:15], s[10:11], s12, v2, 0
	v_lshl_add_u64 v[14:15], v[14:15], 2, v[18:19]
	global_load_dwordx4 v[60:63], v[14:15], off
	v_mad_i64_i32 v[20:21], s[10:11], s12, v8, 0
	v_lshl_add_u64 v[18:19], v[20:21], 2, v[18:19]
	global_load_dwordx4 v[64:67], v[18:19], off
	s_lshl_b32 s4, s4, 11
	s_add_u32 s4, s8, s4
	s_addc_u32 s8, s9, 0
	s_lshl_b64 s[6:7], s[6:7], 1
	s_add_u32 s6, s4, s6
	s_addc_u32 s7, s8, s7
	s_add_i32 s19, s19, s14
	s_add_i32 s15, s15, s16
	s_add_i32 s17, s17, s18
	v_lshl_add_u64 v[76:77], s[6:7], 0, v[6:7]
	v_lshl_add_u64 v[76:77], v[76:77], 0, v[10:11]
	s_bitset1_b32 s20, 4
.Lp0t_issued:
	s_waitcnt vmcnt(0)
	s_bitcmp1_b32 s20, 0
	s_cbranch_scc0 .Lp0t_done
	ds_write2_b32 v3, v24, v25 offset1:1
	ds_write2_b32 v3, v26, v27 offset0:2 offset1:3
	ds_write2_b32 v9, v28, v29 offset1:1
	ds_write2_b32 v12, v30, v31 offset1:1
	s_waitcnt lgkmcnt(0)
	s_barrier
	ds_read2_b32 v[14:15], v1 offset1:65
	ds_read2_b32 v[16:17], v1 offset0:130 offset1:195
	ds_read2_b32 v[18:19], v13 offset0:4 offset1:69
	ds_read2_b32 v[20:21], v13 offset0:134 offset1:199
	s_waitcnt lgkmcnt(3)
	v_cvt_pk_bf16_f32 v14, v14, v15
	s_waitcnt lgkmcnt(2)
	v_cvt_pk_bf16_f32 v15, v16, v17
	s_waitcnt lgkmcnt(1)
	v_cvt_pk_bf16_f32 v16, v18, v19
	s_waitcnt lgkmcnt(0)
	v_cvt_pk_bf16_f32 v17, v20, v21
	global_store_dwordx4 v[68:69], v[14:17], off
	s_barrier
	s_bitcmp1_b32 s20, 1
	s_cbranch_scc0 .Lp0t_done
	ds_write2_b32 v3, v32, v33 offset1:1
	ds_write2_b32 v3, v34, v35 offset0:2 offset1:3
	ds_write2_b32 v9, v36, v37 offset1:1
	ds_write2_b32 v12, v38, v39 offset1:1
	s_waitcnt lgkmcnt(0)
	s_barrier
	ds_read2_b32 v[14:15], v1 offset1:65
	ds_read2_b32 v[16:17], v1 offset0:130 offset1:195
	ds_read2_b32 v[18:19], v13 offset0:4 offset1:69
	ds_read2_b32 v[20:21], v13 offset0:134 offset1:199
	s_waitcnt lgkmcnt(3)
	v_cvt_pk_bf16_f32 v14, v14, v15
	s_waitcnt lgkmcnt(2)
	v_cvt_pk_bf16_f32 v15, v16, v17
	s_waitcnt lgkmcnt(1)
	v_cvt_pk_bf16_f32 v16, v18, v19
	s_waitcnt lgkmcnt(0)
	v_cvt_pk_bf16_f32 v17, v20, v21
	global_store_dwordx4 v[70:71], v[14:17], off
	s_barrier
	s_bitcmp1_b32 s20, 2
	s_cbranch_scc0 .Lp0t_done
	ds_write2_b32 v3, v40, v41 offset1:1
	ds_write2_b32 v3, v42, v43 offset0:2 offset1:3
	ds_write2_b32 v9, v44, v45 offset1:1
	ds_write2_b32 v12, v46, v47 offset1:1
	s_waitcnt lgkmcnt(0)
	s_barrier
	ds_read2_b32 v[14:15], v1 offset1:65
	ds_read2_b32 v[16:17], v1 offset0:130 offset1:195
	ds_read2_b32 v[18:19], v13 offset0:4 offset1:69
	ds_read2_b32 v[20:21], v13 offset0:134 offset1:199
	s_waitcnt lgkmcnt(3)
	v_cvt_pk_bf16_f32 v14, v14, v15
	s_waitcnt lgkmcnt(2)
	v_cvt_pk_bf16_f32 v15, v16, v17
	s_waitcnt lgkmcnt(1)
	v_cvt_pk_bf16_f32 v16, v18, v19
	s_waitcnt lgkmcnt(0)
	v_cvt_pk_bf16_f32 v17, v20, v21
	global_store_dwordx4 v[72:73], v[14:17], off
	s_barrier
	s_bitcmp1_b32 s20, 3
	s_cbranch_scc0 .Lp0t_done
	ds_write2_b32 v3, v52, v53 offset1:1
	ds_write2_b32 v3, v54, v55 offset0:2 offset1:3
	ds_write2_b32 v9, v56, v57 offset1:1
	ds_write2_b32 v12, v58, v59 offset1:1
	s_waitcnt lgkmcnt(0)
	s_barrier
	ds_read2_b32 v[14:15], v1 offset1:65
	ds_read2_b32 v[16:17], v1 offset0:130 offset1:195
	ds_read2_b32 v[18:19], v13 offset0:4 offset1:69
	ds_read2_b32 v[20:21], v13 offset0:134 offset1:199
	s_waitcnt lgkmcnt(3)
	v_cvt_pk_bf16_f32 v14, v14, v15
	s_waitcnt lgkmcnt(2)
	v_cvt_pk_bf16_f32 v15, v16, v17
	s_waitcnt lgkmcnt(1)
	v_cvt_pk_bf16_f32 v16, v18, v19
	s_waitcnt lgkmcnt(0)
	v_cvt_pk_bf16_f32 v17, v20, v21
	global_store_dwordx4 v[74:75], v[14:17], off
	s_barrier
	s_bitcmp1_b32 s20, 4
	s_cbranch_scc0 .Lp0t_done
	ds_write2_b32 v3, v60, v61 offset1:1
	ds_write2_b32 v3, v62, v63 offset0:2 offset1:3
	ds_write2_b32 v9, v64, v65 offset1:1
	ds_write2_b32 v12, v66, v67 offset1:1
	s_waitcnt lgkmcnt(0)
	s_barrier
	ds_read2_b32 v[14:15], v1 offset1:65
	ds_read2_b32 v[16:17], v1 offset0:130 offset1:195
	ds_read2_b32 v[18:19], v13 offset0:4 offset1:69
	ds_read2_b32 v[20:21], v13 offset0:134 offset1:199
	s_waitcnt lgkmcnt(3)
	v_cvt_pk_bf16_f32 v14, v14, v15
	s_waitcnt lgkmcnt(2)
	v_cvt_pk_bf16_f32 v15, v16, v17
	s_waitcnt lgkmcnt(1)
	v_cvt_pk_bf16_f32 v16, v18, v19
	s_waitcnt lgkmcnt(0)
	v_cvt_pk_bf16_f32 v17, v20, v21
	global_store_dwordx4 v[76:77], v[14:17], off
	s_barrier
.Lp0t_done:
	s_cmpk_gt_i32 s19, 0x4ff
	s_cbranch_scc1 .LBB0_13
	s_branch .LBB0_9

;     __host__ __device__ bool next(int i, Unit& u) const {
;         const long L = (long)i * G + c; if (L >= nwg) return false;
;         int wgid = (int)L; { const int q = nwg / NXCD, r = nwg % NXCD, xcd = wgid % NXCD, off = wgid / NXCD; wgid = (xcd < r ? xcd * (q + 1) : r * (q + 1) + (xcd - r) * q) + off; }
;         const int nig = WGM * nN, gid = wgid / nig, fm = gid * WGM, gsz = (nM - fm) < WGM ? (nM - fm) : WGM;
;         u.pm = fm + ((wgid % nig) % gsz); u.pn = (wgid % nig) / gsz; return true;
;     }
.LBB0_610:
	s_add_i32 s8, s8, 1
	s_mul_i32 s19, s8, s9
	s_mul_hi_u32 s20, s8, s33
	s_add_i32 s20, s20, s19
	s_mul_i32 s19, s8, s33
	s_add_u32 s90, s19, s2
	s_addc_u32 s91, s20, s10
	s_mov_b32 s101, 15
	s_cmp_lg_u32 s8, 1
	s_cbranch_scc1 .Lp3q_hdr_done
	s_and_b32 s19, s2, 7
	s_mul_i32 s19, s19, 6
	s_lshr_b32 s90, s2, 3
	s_add_i32 s19, s19, s90
	s_lshr_b32 s90, s19, 2
	s_add_i32 s90, s90, 0x100
	s_cmp_lt_u32 s2, 48
	s_cselect_b32 s90, s90, 0x7fffffff
	s_mov_b32 s91, 0
	s_and_b32 s19, s19, 3
	s_lshl_b32 s101, 1, s19
